# speedup vs baseline: 1.0222x; 1.0017x over previous
; #define STAGE_A(Poff, off, hrow) do { const unsigned _s = (off) + (unsigned)(hrow) * lda2;                                \
;     GLDS(ldsw + (Poff), offA, srdA, _s); GLDS(ldsw + (Poff) + 8192, offA, srdA, _s + lda128); } while (0)
; #define STAGE_B(Poff, off, hrow) do { const unsigned _s = (off) + (unsigned)(hrow) * ldb2;                                \
;     GLDS(ldsw + (Poff), offB, srdB, _s); GLDS(ldsw + (Poff) + 8192, offB, srdB, _s + ldb128); } while (0)
; #define WAIT_V(n) asm volatile("s_waitcnt vmcnt(" #n ")" ::: "memory")
; #define BAR __builtin_amdgcn_s_barrier()
; __device__ __forceinline__ void gemm_phase(const int tid_, const GemmArgs& ga, u16* shm) {
;     ...
;     const int wid = tid_ >> 6, lane = tid_ & 63, wr = wid >> 2, wc = wid & 3, fr = lane & 15, fq = lane >> 4;
;     int sr_, sc_; stage_rc(tid_ * 16, sr_, sc_);
;     const unsigned offA = (unsigned)(sr_ * lda + sc_) * 2u, offB = (unsigned)(sr_ * ldb + sc_) * 2u;
;     const int obs = lds_byte(fr, fq * 8);
;     const int aoff = wr * 8192 + obs, boff = wc * 4096 + obs;
;     f32x4 acc[2][2][4][2] = {};
;     bf16x8 At[4][2], B0[2][2], B1[2][2];
;     int brow, bcol; tile_coords(w, nM, nN, brow, bcol);
;     const unsigned lda2 = (unsigned)lda * 2u, ldb2 = (unsigned)ldb * 2u, lda128 = (unsigned)lda * 128u, ldb128 = (unsigned)ldb * 128u;
;     const __amdgpu_buffer_rsrc_t srdA = __builtin_amdgcn_make_buffer_rsrc((void*)ga.A, (short)0, 0x7fffffff, 0x00020000);
;     const __amdgpu_buffer_rsrc_t srdB = __builtin_amdgcn_make_buffer_rsrc((void*)ga.Bt, (short)0, 0x7fffffff, 0x00020000);
;     const unsigned ldsw = (unsigned)(uintptr_t)shm + (unsigned)__builtin_amdgcn_readfirstlane(wid) * 1024u;
;     unsigned gA = ((unsigned)brow * (unsigned)lda + (ga.agrp ? (unsigned)((bcol >> 9) << 9) : 0u)) * 2u;
;     unsigned gB = (unsigned)bcol * ldb2;
;     STAGE_B(SBO(0, 0), gB, 0); STAGE_A(SAO(0, 0), gA, 0);
;     STAGE_B(SBO(0, 1), gB, HALF); STAGE_A(SAO(0, 1), gA, HALF);
;     if (wr == 1) BAR;
;     WAIT_V(4); BAR;
;     STAGE_B(SBO(1, 0), gB + 128, 0); STAGE_A(SAO(1, 0), gA + 128, 0); STAGE_B(SBO(1, 1), gB + 128, HALF);
;     WAIT_V(6); BAR;
.LBB0_310:
	s_or_b64 exec, exec, s[4:5]
	v_and_b32_e32 v1, 15, v186
	v_lshlrev_b32_e32 v4, 2, v186
	v_and_b32_e32 v2, 48, v186
	v_lshlrev_b32_e32 v1, 6, v1
	v_and_b32_e32 v4, 32, v4
	v_or_b32_e32 v3, v1, v2
	v_bitop3_b32 v1, v1, v4, v2 bitop3:0x36
	v_lshlrev_b32_e32 v0, 12, v0
	s_movk_i32 s4, 0x3000
	v_and_or_b32 v0, v0, s4, v1
	v_readlane_b32 s4, v250, 52
	s_lshr_b32 s67, s60, 6
	s_lshl_b32 s4, s4, 8
	s_or_b32 s5, s1, 0x80
	s_cmp_lg_u32 0, -1
	s_cselect_b32 s7, 0, 0
	s_add_i32 s6, s7, s6
	s_waitcnt vmcnt(0)
	s_barrier
	s_add_i32 s98, s6, 0x18000
	s_mov_b32 s46, s38
	s_mov_b32 s47, s39
	s_mov_b32 m0, s98
	s_nop 0
	buffer_load_dwordx4 v223, s[44:47], s5 offen lds
	s_add_i32 s99, s6, 0x1a000
	s_add_i32 s5, s5, s63
	s_mov_b32 m0, s99
	s_nop 0
	buffer_load_dwordx4 v223, s[44:47], s5 offen lds
	s_or_b32 s7, s54, 0x80
	s_add_i32 s68, s6, 0x8000
	s_mov_b32 s50, s38
	s_mov_b32 s51, s39
	s_mov_b32 m0, s68
	s_nop 0
	buffer_load_dwordx4 v222, s[48:51], s7 offen lds
	s_add_i32 s69, s6, 0xa000
	s_add_i32 s7, s7, s62
	s_mov_b32 m0, s69
	s_nop 0
	buffer_load_dwordx4 v222, s[48:51], s7 offen lds
	s_add_i32 s5, s5, s63
	s_add_i32 s42, s6, 0x1c000
	s_mov_b32 m0, s42
	s_nop 0
	buffer_load_dwordx4 v223, s[44:47], s5 offen lds
	v_lshlrev_b32_e32 v2, 13, v151
	s_add_i32 s43, s6, 0x1e000
	s_add_i32 s5, s5, s63
	s_mov_b32 m0, s43
	s_nop 0
	buffer_load_dwordx4 v223, s[44:47], s5 offen lds
	v_bitop3_b32 v2, v3, v2, v4 bitop3:0xde
	s_waitcnt vmcnt(6)
	v_mov_b32_e32 v96, v97
	v_mov_b32_e32 v98, v97
	v_mov_b32_e32 v99, v97
	v_add_u32_e32 v224, 0, v0
	v_add_u32_e32 v225, 0, v2
	v_mov_b64_e32 v[0:1], v[96:97]
	v_mov_b64_e32 v[4:5], v[96:97]
	v_mov_b64_e32 v[8:9], v[96:97]
	v_mov_b64_e32 v[12:13], v[96:97]
	v_mov_b64_e32 v[16:17], v[96:97]
	v_mov_b64_e32 v[20:21], v[96:97]
	v_mov_b64_e32 v[24:25], v[96:97]
	v_mov_b64_e32 v[28:29], v[96:97]
	v_mov_b64_e32 v[32:33], v[96:97]
	v_mov_b64_e32 v[36:37], v[96:97]
	v_mov_b64_e32 v[40:41], v[96:97]
	v_mov_b64_e32 v[44:45], v[96:97]
	v_mov_b64_e32 v[48:49], v[96:97]
	v_mov_b64_e32 v[52:53], v[96:97]
	v_mov_b64_e32 v[56:57], v[96:97]
	v_mov_b64_e32 v[60:61], v[96:97]
	v_mov_b64_e32 v[64:65], v[96:97]
	v_mov_b64_e32 v[68:69], v[96:97]
	v_mov_b64_e32 v[72:73], v[96:97]
	v_mov_b64_e32 v[76:77], v[96:97]
	v_mov_b64_e32 v[80:81], v[96:97]
	v_mov_b64_e32 v[84:85], v[96:97]
	v_mov_b64_e32 v[88:89], v[96:97]
	v_mov_b64_e32 v[92:93], v[96:97]
	v_mov_b64_e32 v[102:103], v[98:99]
	v_mov_b64_e32 v[106:107], v[98:99]
	v_mov_b64_e32 v[110:111], v[98:99]
	v_mov_b64_e32 v[114:115], v[98:99]
	v_mov_b64_e32 v[118:119], v[98:99]
	v_mov_b64_e32 v[122:123], v[98:99]
	v_mov_b64_e32 v[126:127], v[98:99]
	v_mov_b64_e32 v[130:131], v[98:99]
	s_bitset1_b32 s4, 7
	s_add_i32 s66, s6, 0xc000
	s_add_i32 s18, s6, 0xe000
	v_mov_b64_e32 v[2:3], v[98:99]
	v_mov_b64_e32 v[6:7], v[98:99]
	v_mov_b64_e32 v[10:11], v[98:99]
	v_mov_b64_e32 v[14:15], v[98:99]
	v_mov_b64_e32 v[18:19], v[98:99]
	v_mov_b64_e32 v[22:23], v[98:99]
	v_mov_b64_e32 v[26:27], v[98:99]
	v_mov_b64_e32 v[30:31], v[98:99]
	v_mov_b64_e32 v[34:35], v[98:99]
	v_mov_b64_e32 v[38:39], v[98:99]
	v_mov_b64_e32 v[42:43], v[98:99]
	v_mov_b64_e32 v[46:47], v[98:99]
	v_mov_b64_e32 v[50:51], v[98:99]
	v_mov_b64_e32 v[54:55], v[98:99]
	s_mov_b32 s6, s3
	v_mov_b64_e32 v[58:59], v[98:99]
	v_mov_b64_e32 v[62:63], v[98:99]
	v_mov_b64_e32 v[66:67], v[98:99]
	v_mov_b64_e32 v[70:71], v[98:99]
	v_mov_b64_e32 v[74:75], v[98:99]
	v_mov_b64_e32 v[78:79], v[98:99]
	v_mov_b64_e32 v[82:83], v[98:99]
	v_mov_b64_e32 v[86:87], v[98:99]
	v_mov_b64_e32 v[90:91], v[98:99]
	v_mov_b64_e32 v[94:95], v[98:99]
	v_mov_b64_e32 v[100:101], v[96:97]
	v_mov_b64_e32 v[104:105], v[96:97]
	v_mov_b64_e32 v[108:109], v[96:97]
	v_mov_b64_e32 v[112:113], v[96:97]
	v_mov_b64_e32 v[116:117], v[96:97]
	v_mov_b64_e32 v[120:121], v[96:97]
	v_mov_b64_e32 v[124:125], v[96:97]
	v_mov_b64_e32 v[128:129], v[96:97]
	s_barrier
	v_writelane_b32 v250, s4, 58
	s_branch .LBB0_312
